# xcd barrier: L1 invalidate (buffer_inv sc1) issued at arrival instead of after release; no loads between arrival and exit
# speedup vs baseline: 1.0690x; 1.0095x over previous
; __device__ __forceinline__ unsigned xb_ld(unsigned* p)              { return __hip_atomic_load(p, __ATOMIC_RELAXED, __HIP_MEMORY_SCOPE_AGENT); }
; __device__ __forceinline__ unsigned xb_add(unsigned* p, unsigned v) { return __hip_atomic_fetch_add(p, v, __ATOMIC_RELAXED, __HIP_MEMORY_SCOPE_AGENT); }
; #define XB_SPIN(cond, bar) do { unsigned _sp = 0; while (cond) { __builtin_amdgcn_s_sleep(1); \
;     if ((++_sp & 255u) == 0u) { if (xb_ld(&(bar)[XB_TMO])) break; if (_sp > XB_SPIN_CAP) { atomicAdd(&(bar)[XB_TMO], 1u); break; } } } } while (0)
; __device__ __forceinline__ void xcd_barrier(const XcdBarrier& b) {
;     ...
;         __builtin_amdgcn_s_waitcnt(0);
;         unsigned nloc = b.st[0], nx = b.st[1];
;         if (nloc == 0u) { xcd_barrier_complete(bar, b.x, nloc, nx); b.st[0] = nloc; b.st[1] = nx; }
;         const unsigned old = xb_add(&bar[XB_XSUB(b.x)], 1u);
;         const unsigned gen = old / nloc;
;         if (old + 1u == (gen + 1u) * nloc) {
;             __builtin_amdgcn_fence(__ATOMIC_RELEASE, "agent");
;             asm volatile("s_waitcnt vmcnt(0)" ::: "memory");
;             const unsigned og = xb_add(&bar[XB_TOP], 1u);
;             const unsigned tg = og / nx;
;             if (og + 1u == (tg + 1u) * nx) xb_add(&bar[XB_TOPGEN], 1u);
;             else XB_SPIN(xb_ld(&bar[XB_TOPGEN]) == tg, bar);
;             __builtin_amdgcn_fence(__ATOMIC_ACQUIRE, "agent");
;             xb_add(&bar[XB_XGEN(b.x)], 1u);
;             asm volatile("s_waitcnt vmcnt(0)" ::: "memory");
;         } else {
;             XB_SPIN(xb_ld(&bar[XB_XGEN(b.x)]) == gen, bar);
.LBB0_127:
	s_or_b64 exec, exec, s[12:13]
	v_cvt_f32_u32_e32 v4, v2
	s_waitcnt vmcnt(0)
	buffer_inv sc1
	v_readfirstlane_b32 s4, v3
	v_sub_u32_e32 v3, 0, v2
	v_rcp_iflag_f32_e32 v4, v4
	v_add_u32_e32 v5, s4, v1
	v_mul_f32_e32 v4, 0x4f7ffffe, v4
	v_cvt_u32_f32_e32 v4, v4
	v_mul_lo_u32 v1, v3, v4
	v_mul_hi_u32 v1, v4, v1
	v_add_u32_e32 v1, v4, v1
	v_mul_hi_u32 v1, v5, v1
	v_mul_lo_u32 v3, v1, v2
	v_sub_u32_e32 v3, v5, v3
	v_add_u32_e32 v4, 1, v1
	v_cmp_ge_u32_e32 vcc, v3, v2
	s_nop 1
	v_cndmask_b32_e32 v1, v1, v4, vcc
	v_sub_u32_e32 v4, v3, v2
	v_cndmask_b32_e32 v3, v3, v4, vcc
	v_add_u32_e32 v4, 1, v1
	v_cmp_ge_u32_e32 vcc, v3, v2
	v_add_u32_e32 v3, 1, v5
	s_nop 0
	v_cndmask_b32_e32 v1, v1, v4, vcc
	v_mul_lo_u32 v4, v2, v1
	v_add_u32_e32 v2, v4, v2
	v_cmp_ne_u32_e32 vcc, v3, v2
	s_and_saveexec_b64 s[4:5], vcc
	s_xor_b64 s[4:5], exec, s[4:5]
	s_cbranch_execz .LBB0_141
	s_waitcnt lgkmcnt(0)
	v_mov_b32_e32 v0, 0x2000
	global_load_dword v0, v0, s[2:3] offset:1024 sc1
	s_add_u32 s16, s2, 0x2400
	s_addc_u32 s17, s3, 0
	s_waitcnt vmcnt(0)
	v_cmp_eq_u32_e32 vcc, v0, v1
	s_and_saveexec_b64 s[12:13], vcc
	s_cbranch_execz .LBB0_140
	s_add_u32 s14, s66, 0x4200
	s_addc_u32 s15, s67, 0
	s_mov_b32 s28, 1
	s_mov_b64 s[18:19], 0
	v_mov_b32_e32 v0, 0
	s_branch .LBB0_131

; __device__ __forceinline__ unsigned xb_ld(unsigned* p)              { return __hip_atomic_load(p, __ATOMIC_RELAXED, __HIP_MEMORY_SCOPE_AGENT); }
; #define XB_SPIN(cond, bar) do { unsigned _sp = 0; while (cond) { __builtin_amdgcn_s_sleep(1); \
;     if ((++_sp & 255u) == 0u) { if (xb_ld(&(bar)[XB_TMO])) break; if (_sp > XB_SPIN_CAP) { atomicAdd(&(bar)[XB_TMO], 1u); break; } } } } while (0)
; __device__ __forceinline__ void xcd_barrier(const XcdBarrier& b) {
;     ...
;             XB_SPIN(xb_ld(&bar[XB_XGEN(b.x)]) == gen, bar);
;             __builtin_amdgcn_fence(__ATOMIC_ACQUIRE, "agent");
;             asm volatile("s_waitcnt vmcnt(0)" ::: "memory");
.LBB0_140:
	s_or_b64 exec, exec, s[12:13]
	s_waitcnt vmcnt(0)
	s_waitcnt vmcnt(0)

; __device__ __forceinline__ unsigned xb_add(unsigned* p, unsigned v) { return __hip_atomic_fetch_add(p, v, __ATOMIC_RELAXED, __HIP_MEMORY_SCOPE_AGENT); }
; __device__ __forceinline__ void xcd_barrier(const XcdBarrier& b) {
;     ...
;             __builtin_amdgcn_fence(__ATOMIC_ACQUIRE, "agent");
;             xb_add(&bar[XB_XGEN(b.x)], 1u);
;             asm volatile("s_waitcnt vmcnt(0)" ::: "memory");
.LBB0_158:
	s_or_b64 exec, exec, s[4:5]
	s_mov_b64 s[4:5], exec
	v_mbcnt_lo_u32_b32 v0, s4, 0
	v_mbcnt_hi_u32_b32 v0, s5, v0
	v_cmp_eq_u32_e32 vcc, 0, v0
	s_waitcnt vmcnt(0)
	s_waitcnt vmcnt(0)

; __device__ __forceinline__ unsigned xb_ld(unsigned* p)              { return __hip_atomic_load(p, __ATOMIC_RELAXED, __HIP_MEMORY_SCOPE_AGENT); }
; __device__ __forceinline__ unsigned xb_add(unsigned* p, unsigned v) { return __hip_atomic_fetch_add(p, v, __ATOMIC_RELAXED, __HIP_MEMORY_SCOPE_AGENT); }
; #define XB_SPIN(cond, bar) do { unsigned _sp = 0; while (cond) { __builtin_amdgcn_s_sleep(1); \
;     if ((++_sp & 255u) == 0u) { if (xb_ld(&(bar)[XB_TMO])) break; if (_sp > XB_SPIN_CAP) { atomicAdd(&(bar)[XB_TMO], 1u); break; } } } } while (0)
; __device__ __forceinline__ void xcd_barrier(const XcdBarrier& b) {
;     ...
;         __builtin_amdgcn_s_waitcnt(0);
;         unsigned nloc = b.st[0], nx = b.st[1];
;         if (nloc == 0u) { xcd_barrier_complete(bar, b.x, nloc, nx); b.st[0] = nloc; b.st[1] = nx; }
;         const unsigned old = xb_add(&bar[XB_XSUB(b.x)], 1u);
;         const unsigned gen = old / nloc;
;         if (old + 1u == (gen + 1u) * nloc) {
;             __builtin_amdgcn_fence(__ATOMIC_RELEASE, "agent");
;             asm volatile("s_waitcnt vmcnt(0)" ::: "memory");
;             const unsigned og = xb_add(&bar[XB_TOP], 1u);
;             const unsigned tg = og / nx;
;             if (og + 1u == (tg + 1u) * nx) xb_add(&bar[XB_TOPGEN], 1u);
;             else XB_SPIN(xb_ld(&bar[XB_TOPGEN]) == tg, bar);
;             __builtin_amdgcn_fence(__ATOMIC_ACQUIRE, "agent");
;             xb_add(&bar[XB_XGEN(b.x)], 1u);
;             asm volatile("s_waitcnt vmcnt(0)" ::: "memory");
;         } else {
;             XB_SPIN(xb_ld(&bar[XB_XGEN(b.x)]) == gen, bar);
.LBB0_988:
	s_or_b64 exec, exec, s[16:17]
	v_cvt_f32_u32_e32 v4, v2
	s_waitcnt vmcnt(0)
	buffer_inv sc1
	v_readfirstlane_b32 s10, v3
	v_sub_u32_e32 v3, 0, v2
	v_rcp_iflag_f32_e32 v4, v4
	v_add_u32_e32 v5, s10, v1
	v_mul_f32_e32 v4, 0x4f7ffffe, v4
	v_cvt_u32_f32_e32 v4, v4
	v_mul_lo_u32 v1, v3, v4
	v_mul_hi_u32 v1, v4, v1
	v_add_u32_e32 v1, v4, v1
	v_mul_hi_u32 v1, v5, v1
	v_mul_lo_u32 v3, v1, v2
	v_sub_u32_e32 v3, v5, v3
	v_add_u32_e32 v4, 1, v1
	v_cmp_ge_u32_e32 vcc, v3, v2
	s_nop 1
	v_cndmask_b32_e32 v1, v1, v4, vcc
	v_sub_u32_e32 v4, v3, v2
	v_cndmask_b32_e32 v3, v3, v4, vcc
	v_add_u32_e32 v4, 1, v1
	v_cmp_ge_u32_e32 vcc, v3, v2
	v_add_u32_e32 v3, 1, v5
	s_nop 0
	v_cndmask_b32_e32 v1, v1, v4, vcc
	v_mul_lo_u32 v4, v2, v1
	v_add_u32_e32 v2, v4, v2
	v_cmp_ne_u32_e32 vcc, v3, v2
	s_and_saveexec_b64 s[10:11], vcc
	s_xor_b64 s[10:11], exec, s[10:11]
	s_cbranch_execz .LBB0_1002
	s_waitcnt lgkmcnt(0)
	v_mov_b32_e32 v0, 0x2000
	global_load_dword v0, v0, s[4:5] offset:1024 sc1
	s_add_u32 s20, s4, 0x2400
	s_addc_u32 s21, s5, 0
	s_waitcnt vmcnt(0)
	v_cmp_eq_u32_e32 vcc, v0, v1
	s_and_saveexec_b64 s[16:17], vcc
	s_cbranch_execz .LBB0_1001
	s_add_u32 s18, s66, 0x4200
	s_addc_u32 s19, s67, 0
	s_mov_b32 s33, 1
	s_mov_b64 s[22:23], 0
	v_mov_b32_e32 v0, 0
	s_branch .LBB0_992

; __device__ __forceinline__ unsigned xb_ld(unsigned* p)              { return __hip_atomic_load(p, __ATOMIC_RELAXED, __HIP_MEMORY_SCOPE_AGENT); }
; #define XB_SPIN(cond, bar) do { unsigned _sp = 0; while (cond) { __builtin_amdgcn_s_sleep(1); \
;     if ((++_sp & 255u) == 0u) { if (xb_ld(&(bar)[XB_TMO])) break; if (_sp > XB_SPIN_CAP) { atomicAdd(&(bar)[XB_TMO], 1u); break; } } } } while (0)
; __device__ __forceinline__ void xcd_barrier(const XcdBarrier& b) {
;     ...
;             XB_SPIN(xb_ld(&bar[XB_XGEN(b.x)]) == gen, bar);
;             __builtin_amdgcn_fence(__ATOMIC_ACQUIRE, "agent");
;             asm volatile("s_waitcnt vmcnt(0)" ::: "memory");
.LBB0_1001:
	s_or_b64 exec, exec, s[16:17]
	s_waitcnt vmcnt(0)
	s_waitcnt vmcnt(0)

; __device__ __forceinline__ unsigned xb_add(unsigned* p, unsigned v) { return __hip_atomic_fetch_add(p, v, __ATOMIC_RELAXED, __HIP_MEMORY_SCOPE_AGENT); }
; __device__ __forceinline__ void xcd_barrier(const XcdBarrier& b) {
;     ...
;             __builtin_amdgcn_fence(__ATOMIC_ACQUIRE, "agent");
;             xb_add(&bar[XB_XGEN(b.x)], 1u);
;             asm volatile("s_waitcnt vmcnt(0)" ::: "memory");
.LBB0_1019:
	s_or_b64 exec, exec, s[10:11]
	s_mov_b64 s[10:11], exec
	v_mbcnt_lo_u32_b32 v0, s10, 0
	v_mbcnt_hi_u32_b32 v0, s11, v0
	v_cmp_eq_u32_e32 vcc, 0, v0
	s_waitcnt vmcnt(0)
	s_waitcnt vmcnt(0)

; __device__ __forceinline__ unsigned xb_ld(unsigned* p)              { return __hip_atomic_load(p, __ATOMIC_RELAXED, __HIP_MEMORY_SCOPE_AGENT); }
; __device__ __forceinline__ unsigned xb_add(unsigned* p, unsigned v) { return __hip_atomic_fetch_add(p, v, __ATOMIC_RELAXED, __HIP_MEMORY_SCOPE_AGENT); }
; #define XB_SPIN(cond, bar) do { unsigned _sp = 0; while (cond) { __builtin_amdgcn_s_sleep(1); \
;     if ((++_sp & 255u) == 0u) { if (xb_ld(&(bar)[XB_TMO])) break; if (_sp > XB_SPIN_CAP) { atomicAdd(&(bar)[XB_TMO], 1u); break; } } } } while (0)
; __device__ __forceinline__ void xcd_barrier(const XcdBarrier& b) {
;     ...
;         __builtin_amdgcn_s_waitcnt(0);
;         unsigned nloc = b.st[0], nx = b.st[1];
;         if (nloc == 0u) { xcd_barrier_complete(bar, b.x, nloc, nx); b.st[0] = nloc; b.st[1] = nx; }
;         const unsigned old = xb_add(&bar[XB_XSUB(b.x)], 1u);
;         const unsigned gen = old / nloc;
;         if (old + 1u == (gen + 1u) * nloc) {
;             __builtin_amdgcn_fence(__ATOMIC_RELEASE, "agent");
;             asm volatile("s_waitcnt vmcnt(0)" ::: "memory");
;             const unsigned og = xb_add(&bar[XB_TOP], 1u);
;             const unsigned tg = og / nx;
;             if (og + 1u == (tg + 1u) * nx) xb_add(&bar[XB_TOPGEN], 1u);
;             else XB_SPIN(xb_ld(&bar[XB_TOPGEN]) == tg, bar);
;             __builtin_amdgcn_fence(__ATOMIC_ACQUIRE, "agent");
;             xb_add(&bar[XB_XGEN(b.x)], 1u);
;             asm volatile("s_waitcnt vmcnt(0)" ::: "memory");
;         } else {
;             XB_SPIN(xb_ld(&bar[XB_XGEN(b.x)]) == gen, bar);
.LBB0_1064:
	s_or_b64 exec, exec, s[8:9]
	v_cvt_f32_u32_e32 v4, v2
	s_waitcnt vmcnt(0)
	buffer_inv sc1
	v_readfirstlane_b32 s6, v3
	v_sub_u32_e32 v3, 0, v2
	v_rcp_iflag_f32_e32 v4, v4
	v_add_u32_e32 v5, s6, v1
	v_mul_f32_e32 v4, 0x4f7ffffe, v4
	v_cvt_u32_f32_e32 v4, v4
	v_mul_lo_u32 v1, v3, v4
	v_mul_hi_u32 v1, v4, v1
	v_add_u32_e32 v1, v4, v1
	v_mul_hi_u32 v1, v5, v1
	v_mul_lo_u32 v3, v1, v2
	v_sub_u32_e32 v3, v5, v3
	v_add_u32_e32 v4, 1, v1
	v_cmp_ge_u32_e32 vcc, v3, v2
	s_nop 1
	v_cndmask_b32_e32 v1, v1, v4, vcc
	v_sub_u32_e32 v4, v3, v2
	v_cndmask_b32_e32 v3, v3, v4, vcc
	v_add_u32_e32 v4, 1, v1
	v_cmp_ge_u32_e32 vcc, v3, v2
	v_add_u32_e32 v3, 1, v5
	s_nop 0
	v_cndmask_b32_e32 v1, v1, v4, vcc
	v_mul_lo_u32 v4, v2, v1
	v_add_u32_e32 v2, v4, v2
	v_cmp_ne_u32_e32 vcc, v3, v2
	s_and_saveexec_b64 s[6:7], vcc
	s_xor_b64 s[6:7], exec, s[6:7]
	s_cbranch_execz .LBB0_1078
	s_waitcnt lgkmcnt(0)
	v_mov_b32_e32 v0, 0x2000
	global_load_dword v0, v0, s[4:5] offset:1024 sc1
	s_add_u32 s14, s4, 0x2400
	s_addc_u32 s15, s5, 0
	s_waitcnt vmcnt(0)
	v_cmp_eq_u32_e32 vcc, v0, v1
	s_and_saveexec_b64 s[8:9], vcc
	s_cbranch_execz .LBB0_1077
	s_add_u32 s10, s66, 0x4200
	s_addc_u32 s11, s67, 0
	s_mov_b32 s26, 1
	s_mov_b64 s[16:17], 0
	v_mov_b32_e32 v0, 0
	s_branch .LBB0_1068

; __device__ __forceinline__ unsigned xb_ld(unsigned* p)              { return __hip_atomic_load(p, __ATOMIC_RELAXED, __HIP_MEMORY_SCOPE_AGENT); }
; __device__ __forceinline__ unsigned xb_add(unsigned* p, unsigned v) { return __hip_atomic_fetch_add(p, v, __ATOMIC_RELAXED, __HIP_MEMORY_SCOPE_AGENT); }
; #define XB_SPIN(cond, bar) do { unsigned _sp = 0; while (cond) { __builtin_amdgcn_s_sleep(1); \
;     if ((++_sp & 255u) == 0u) { if (xb_ld(&(bar)[XB_TMO])) break; if (_sp > XB_SPIN_CAP) { atomicAdd(&(bar)[XB_TMO], 1u); break; } } } } while (0)
; __device__ __forceinline__ void xcd_barrier(const XcdBarrier& b) {
;     ...
;             __builtin_amdgcn_fence(__ATOMIC_ACQUIRE, "agent");
;             xb_add(&bar[XB_XGEN(b.x)], 1u);
;             asm volatile("s_waitcnt vmcnt(0)" ::: "memory");
;         } else {
;             XB_SPIN(xb_ld(&bar[XB_XGEN(b.x)]) == gen, bar);
;             __builtin_amdgcn_fence(__ATOMIC_ACQUIRE, "agent");
;             asm volatile("s_waitcnt vmcnt(0)" ::: "memory");
;         }
.LBB0_1077:
	s_or_b64 exec, exec, s[8:9]
	s_waitcnt vmcnt(0)
	s_waitcnt vmcnt(0)

; __device__ __forceinline__ unsigned xb_add(unsigned* p, unsigned v) { return __hip_atomic_fetch_add(p, v, __ATOMIC_RELAXED, __HIP_MEMORY_SCOPE_AGENT); }
; __device__ __forceinline__ void xcd_barrier(const XcdBarrier& b) {
;     ...
;             __builtin_amdgcn_fence(__ATOMIC_ACQUIRE, "agent");
;             xb_add(&bar[XB_XGEN(b.x)], 1u);
;             asm volatile("s_waitcnt vmcnt(0)" ::: "memory");
.LBB0_1095:
	s_or_b64 exec, exec, s[6:7]
	s_mov_b64 s[6:7], exec
	v_mbcnt_lo_u32_b32 v0, s6, 0
	v_mbcnt_hi_u32_b32 v0, s7, v0
	v_cmp_eq_u32_e32 vcc, 0, v0
	s_waitcnt vmcnt(0)
	s_waitcnt vmcnt(0)

; __device__ __forceinline__ unsigned xb_ld(unsigned* p)              { return __hip_atomic_load(p, __ATOMIC_RELAXED, __HIP_MEMORY_SCOPE_AGENT); }
; __device__ __forceinline__ unsigned xb_add(unsigned* p, unsigned v) { return __hip_atomic_fetch_add(p, v, __ATOMIC_RELAXED, __HIP_MEMORY_SCOPE_AGENT); }
; #define XB_SPIN(cond, bar) do { unsigned _sp = 0; while (cond) { __builtin_amdgcn_s_sleep(1); \
;     if ((++_sp & 255u) == 0u) { if (xb_ld(&(bar)[XB_TMO])) break; if (_sp > XB_SPIN_CAP) { atomicAdd(&(bar)[XB_TMO], 1u); break; } } } } while (0)
; __device__ __forceinline__ void xcd_barrier(const XcdBarrier& b) {
;     ...
;         const unsigned old = xb_add(&bar[XB_XSUB(b.x)], 1u);
;         const unsigned gen = old / nloc;
;         if (old + 1u == (gen + 1u) * nloc) {
;             __builtin_amdgcn_fence(__ATOMIC_RELEASE, "agent");
;             asm volatile("s_waitcnt vmcnt(0)" ::: "memory");
;             const unsigned og = xb_add(&bar[XB_TOP], 1u);
;             const unsigned tg = og / nx;
;             if (og + 1u == (tg + 1u) * nx) xb_add(&bar[XB_TOPGEN], 1u);
;             else XB_SPIN(xb_ld(&bar[XB_TOPGEN]) == tg, bar);
;             __builtin_amdgcn_fence(__ATOMIC_ACQUIRE, "agent");
;             xb_add(&bar[XB_XGEN(b.x)], 1u);
;             asm volatile("s_waitcnt vmcnt(0)" ::: "memory");
;         } else {
;             XB_SPIN(xb_ld(&bar[XB_XGEN(b.x)]) == gen, bar);
.LBB0_1244:
	s_or_b64 exec, exec, s[10:11]
	v_cvt_f32_u32_e32 v4, v2
	s_waitcnt vmcnt(0)
	buffer_inv sc1
	v_readfirstlane_b32 s8, v3
	v_sub_u32_e32 v3, 0, v2
	v_rcp_iflag_f32_e32 v4, v4
	v_add_u32_e32 v5, s8, v1
	v_mul_f32_e32 v4, 0x4f7ffffe, v4
	v_cvt_u32_f32_e32 v4, v4
	v_mul_lo_u32 v1, v3, v4
	v_mul_hi_u32 v1, v4, v1
	v_add_u32_e32 v1, v4, v1
	v_mul_hi_u32 v1, v5, v1
	v_mul_lo_u32 v3, v1, v2
	v_sub_u32_e32 v3, v5, v3
	v_add_u32_e32 v4, 1, v1
	v_cmp_ge_u32_e32 vcc, v3, v2
	s_nop 1
	v_cndmask_b32_e32 v1, v1, v4, vcc
	v_sub_u32_e32 v4, v3, v2
	v_cndmask_b32_e32 v3, v3, v4, vcc
	v_add_u32_e32 v4, 1, v1
	v_cmp_ge_u32_e32 vcc, v3, v2
	v_add_u32_e32 v3, 1, v5
	s_nop 0
	v_cndmask_b32_e32 v1, v1, v4, vcc
	v_mul_lo_u32 v4, v2, v1
	v_add_u32_e32 v2, v4, v2
	v_cmp_ne_u32_e32 vcc, v3, v2
	s_and_saveexec_b64 s[8:9], vcc
	s_xor_b64 s[8:9], exec, s[8:9]
	s_cbranch_execz .LBB0_1258
	s_waitcnt lgkmcnt(0)
	v_mov_b32_e32 v0, 0x2000
	global_load_dword v0, v0, s[6:7] offset:1024 sc1
	s_add_u32 s14, s6, 0x2400
	s_addc_u32 s15, s7, 0
	s_waitcnt vmcnt(0)
	v_cmp_eq_u32_e32 vcc, v0, v1
	s_and_saveexec_b64 s[10:11], vcc
	s_cbranch_execz .LBB0_1257
	s_add_u32 s12, s66, 0x4200
	s_addc_u32 s13, s67, 0
	s_mov_b32 s26, 1
	s_mov_b64 s[16:17], 0
	v_mov_b32_e32 v0, 0
	s_branch .LBB0_1248

; __device__ __forceinline__ unsigned xb_ld(unsigned* p)              { return __hip_atomic_load(p, __ATOMIC_RELAXED, __HIP_MEMORY_SCOPE_AGENT); }
; #define XB_SPIN(cond, bar) do { unsigned _sp = 0; while (cond) { __builtin_amdgcn_s_sleep(1); \
;     if ((++_sp & 255u) == 0u) { if (xb_ld(&(bar)[XB_TMO])) break; if (_sp > XB_SPIN_CAP) { atomicAdd(&(bar)[XB_TMO], 1u); break; } } } } while (0)
; __device__ __forceinline__ void xcd_barrier(const XcdBarrier& b) {
;     ...
;             XB_SPIN(xb_ld(&bar[XB_XGEN(b.x)]) == gen, bar);
;             __builtin_amdgcn_fence(__ATOMIC_ACQUIRE, "agent");
;             asm volatile("s_waitcnt vmcnt(0)" ::: "memory");
;         }
.LBB0_1257:
	s_or_b64 exec, exec, s[10:11]
	s_waitcnt vmcnt(0)
	s_waitcnt vmcnt(0)

; __device__ __forceinline__ unsigned xb_add(unsigned* p, unsigned v) { return __hip_atomic_fetch_add(p, v, __ATOMIC_RELAXED, __HIP_MEMORY_SCOPE_AGENT); }
; __device__ __forceinline__ void xcd_barrier(const XcdBarrier& b) {
;     ...
;             __builtin_amdgcn_fence(__ATOMIC_ACQUIRE, "agent");
;             xb_add(&bar[XB_XGEN(b.x)], 1u);
;             asm volatile("s_waitcnt vmcnt(0)" ::: "memory");
.LBB0_1275:
	s_or_b64 exec, exec, s[8:9]
	s_mov_b64 s[8:9], exec
	v_mbcnt_lo_u32_b32 v0, s8, 0
	v_mbcnt_hi_u32_b32 v0, s9, v0
	v_cmp_eq_u32_e32 vcc, 0, v0
	s_waitcnt vmcnt(0)
	s_waitcnt vmcnt(0)

; __device__ __forceinline__ unsigned xb_ld(unsigned* p)              { return __hip_atomic_load(p, __ATOMIC_RELAXED, __HIP_MEMORY_SCOPE_AGENT); }
; __device__ __forceinline__ unsigned xb_add(unsigned* p, unsigned v) { return __hip_atomic_fetch_add(p, v, __ATOMIC_RELAXED, __HIP_MEMORY_SCOPE_AGENT); }
; #define XB_SPIN(cond, bar) do { unsigned _sp = 0; while (cond) { __builtin_amdgcn_s_sleep(1); \
;     if ((++_sp & 255u) == 0u) { if (xb_ld(&(bar)[XB_TMO])) break; if (_sp > XB_SPIN_CAP) { atomicAdd(&(bar)[XB_TMO], 1u); break; } } } } while (0)
; __device__ __forceinline__ void xcd_barrier(const XcdBarrier& b) {
;     ...
;         const unsigned old = xb_add(&bar[XB_XSUB(b.x)], 1u);
;         const unsigned gen = old / nloc;
;         if (old + 1u == (gen + 1u) * nloc) {
;             __builtin_amdgcn_fence(__ATOMIC_RELEASE, "agent");
;             asm volatile("s_waitcnt vmcnt(0)" ::: "memory");
;             const unsigned og = xb_add(&bar[XB_TOP], 1u);
;             const unsigned tg = og / nx;
;             if (og + 1u == (tg + 1u) * nx) xb_add(&bar[XB_TOPGEN], 1u);
;             else XB_SPIN(xb_ld(&bar[XB_TOPGEN]) == tg, bar);
;             __builtin_amdgcn_fence(__ATOMIC_ACQUIRE, "agent");
;             xb_add(&bar[XB_XGEN(b.x)], 1u);
;             asm volatile("s_waitcnt vmcnt(0)" ::: "memory");
;         } else {
;             XB_SPIN(xb_ld(&bar[XB_XGEN(b.x)]) == gen, bar);
.LBB0_1301:
	s_or_b64 exec, exec, s[8:9]
	v_cvt_f32_u32_e32 v4, v2
	s_waitcnt vmcnt(0)
	buffer_inv sc1
	v_readfirstlane_b32 s6, v3
	v_sub_u32_e32 v3, 0, v2
	v_rcp_iflag_f32_e32 v4, v4
	v_add_u32_e32 v5, s6, v1
	v_mul_f32_e32 v4, 0x4f7ffffe, v4
	v_cvt_u32_f32_e32 v4, v4
	v_mul_lo_u32 v1, v3, v4
	v_mul_hi_u32 v1, v4, v1
	v_add_u32_e32 v1, v4, v1
	v_mul_hi_u32 v1, v5, v1
	v_mul_lo_u32 v3, v1, v2
	v_sub_u32_e32 v3, v5, v3
	v_add_u32_e32 v4, 1, v1
	v_cmp_ge_u32_e32 vcc, v3, v2
	s_nop 1
	v_cndmask_b32_e32 v1, v1, v4, vcc
	v_sub_u32_e32 v4, v3, v2
	v_cndmask_b32_e32 v3, v3, v4, vcc
	v_add_u32_e32 v4, 1, v1
	v_cmp_ge_u32_e32 vcc, v3, v2
	v_add_u32_e32 v3, 1, v5
	s_nop 0
	v_cndmask_b32_e32 v1, v1, v4, vcc
	v_mul_lo_u32 v4, v2, v1
	v_add_u32_e32 v2, v4, v2
	v_cmp_ne_u32_e32 vcc, v3, v2
	s_and_saveexec_b64 s[6:7], vcc
	s_xor_b64 s[6:7], exec, s[6:7]
	s_cbranch_execz .LBB0_1315
	s_waitcnt lgkmcnt(0)
	v_mov_b32_e32 v0, 0x2000
	global_load_dword v0, v0, s[4:5] offset:1024 sc1
	s_add_u32 s12, s4, 0x2400
	s_addc_u32 s13, s5, 0
	s_waitcnt vmcnt(0)
	v_cmp_eq_u32_e32 vcc, v0, v1
	s_and_saveexec_b64 s[8:9], vcc
	s_cbranch_execz .LBB0_1314
	s_add_u32 s10, s66, 0x4200
	s_addc_u32 s11, s67, 0
	s_mov_b32 s24, 1
	s_mov_b64 s[14:15], 0
	v_mov_b32_e32 v0, 0
	s_branch .LBB0_1305

; __device__ __forceinline__ unsigned xb_ld(unsigned* p)              { return __hip_atomic_load(p, __ATOMIC_RELAXED, __HIP_MEMORY_SCOPE_AGENT); }
; __device__ __forceinline__ unsigned xb_add(unsigned* p, unsigned v) { return __hip_atomic_fetch_add(p, v, __ATOMIC_RELAXED, __HIP_MEMORY_SCOPE_AGENT); }
; #define XB_SPIN(cond, bar) do { unsigned _sp = 0; while (cond) { __builtin_amdgcn_s_sleep(1); \
;     if ((++_sp & 255u) == 0u) { if (xb_ld(&(bar)[XB_TMO])) break; if (_sp > XB_SPIN_CAP) { atomicAdd(&(bar)[XB_TMO], 1u); break; } } } } while (0)
; __device__ __forceinline__ void xcd_barrier(const XcdBarrier& b) {
;     ...
;         const unsigned old = xb_add(&bar[XB_XSUB(b.x)], 1u);
;         const unsigned gen = old / nloc;
;         if (old + 1u == (gen + 1u) * nloc) {
;             __builtin_amdgcn_fence(__ATOMIC_RELEASE, "agent");
;             asm volatile("s_waitcnt vmcnt(0)" ::: "memory");
;             const unsigned og = xb_add(&bar[XB_TOP], 1u);
;             const unsigned tg = og / nx;
;             if (og + 1u == (tg + 1u) * nx) xb_add(&bar[XB_TOPGEN], 1u);
;             else XB_SPIN(xb_ld(&bar[XB_TOPGEN]) == tg, bar);
;             __builtin_amdgcn_fence(__ATOMIC_ACQUIRE, "agent");
;             xb_add(&bar[XB_XGEN(b.x)], 1u);
;             asm volatile("s_waitcnt vmcnt(0)" ::: "memory");
;         } else {
;             XB_SPIN(xb_ld(&bar[XB_XGEN(b.x)]) == gen, bar);
.LBB0_1563:
	s_or_b64 exec, exec, s[6:7]
	v_cvt_f32_u32_e32 v4, v2
	s_waitcnt vmcnt(0)
	buffer_inv sc1
	v_readfirstlane_b32 s4, v3
	v_sub_u32_e32 v3, 0, v2
	v_rcp_iflag_f32_e32 v4, v4
	v_add_u32_e32 v5, s4, v1
	v_mul_f32_e32 v4, 0x4f7ffffe, v4
	v_cvt_u32_f32_e32 v4, v4
	v_mul_lo_u32 v1, v3, v4
	v_mul_hi_u32 v1, v4, v1
	v_add_u32_e32 v1, v4, v1
	v_mul_hi_u32 v1, v5, v1
	v_mul_lo_u32 v3, v1, v2
	v_sub_u32_e32 v3, v5, v3
	v_add_u32_e32 v4, 1, v1
	v_cmp_ge_u32_e32 vcc, v3, v2
	s_nop 1
	v_cndmask_b32_e32 v1, v1, v4, vcc
	v_sub_u32_e32 v4, v3, v2
	v_cndmask_b32_e32 v3, v3, v4, vcc
	v_add_u32_e32 v4, 1, v1
	v_cmp_ge_u32_e32 vcc, v3, v2
	v_add_u32_e32 v3, 1, v5
	s_nop 0
	v_cndmask_b32_e32 v1, v1, v4, vcc
	v_mul_lo_u32 v4, v2, v1
	v_add_u32_e32 v2, v4, v2
	v_cmp_ne_u32_e32 vcc, v3, v2
	s_and_saveexec_b64 s[4:5], vcc
	s_xor_b64 s[4:5], exec, s[4:5]
	s_cbranch_execz .LBB0_1577
	s_waitcnt lgkmcnt(0)
	v_mov_b32_e32 v0, 0x2000
	global_load_dword v0, v0, s[2:3] offset:1024 sc1
	s_add_u32 s10, s2, 0x2400
	s_addc_u32 s11, s3, 0
	s_waitcnt vmcnt(0)
	v_cmp_eq_u32_e32 vcc, v0, v1
	s_and_saveexec_b64 s[6:7], vcc
	s_cbranch_execz .LBB0_1576
	s_add_u32 s8, s66, 0x4200
	s_addc_u32 s9, s67, 0
	s_mov_b32 s22, 1
	s_mov_b64 s[12:13], 0
	v_mov_b32_e32 v0, 0
	s_branch .LBB0_1567

; __device__ __forceinline__ unsigned xb_ld(unsigned* p)              { return __hip_atomic_load(p, __ATOMIC_RELAXED, __HIP_MEMORY_SCOPE_AGENT); }
; #define XB_SPIN(cond, bar) do { unsigned _sp = 0; while (cond) { __builtin_amdgcn_s_sleep(1); \
;     if ((++_sp & 255u) == 0u) { if (xb_ld(&(bar)[XB_TMO])) break; if (_sp > XB_SPIN_CAP) { atomicAdd(&(bar)[XB_TMO], 1u); break; } } } } while (0)
; __device__ __forceinline__ void xcd_barrier(const XcdBarrier& b) {
;     ...
;             XB_SPIN(xb_ld(&bar[XB_XGEN(b.x)]) == gen, bar);
;             __builtin_amdgcn_fence(__ATOMIC_ACQUIRE, "agent");
;             asm volatile("s_waitcnt vmcnt(0)" ::: "memory");
;         }
.LBB0_1576:
	s_or_b64 exec, exec, s[6:7]
	s_waitcnt vmcnt(0)
	s_waitcnt vmcnt(0)
